# phase-5 sample-row mini GEMM: 8 K-steps of staged loads in flight instead of 4
# speedup vs baseline: 1.0397x; 1.0397x over previous
.LBB0_1307:
	s_cmp_gt_u32 s92, 63
	s_cbranch_scc1 .LBB0_1327
	s_lshl_b32 s1, s92, 3
	s_and_b32 s2, s1, 0xc0
	s_lshr_b32 s3, s92, 2
	v_and_b32_e32 v2, 0x70, v205
	s_waitcnt lgkmcnt(0)
	v_mov_b32_e32 v3, 0
	v_mul_u32_u24_e32 v6, 0x88, v204
	s_and_b32 s0, s92, 7
	s_or_b32 s1, s2, 0x4000
	s_and_b32 s3, s3, 8
	v_lshl_add_u64 v[4:5], s[58:59], 0, v[2:3]
	v_lshl_add_u64 v[10:11], s[96:97], 0, v[2:3]
	v_lshl_add_u32 v8, v6, 1, v2
	s_or_b32 s0, s3, s0
	v_add_u32_e32 v2, s1, v204
	s_lshl_b32 s0, s0, 6
	v_mul_u32_u24_e32 v2, 0xb00, v2
	v_add_u32_e32 v9, s0, v204
	v_lshlrev_b32_e32 v2, 1, v2
	v_lshl_add_u64 v[6:7], v[4:5], 0, v[2:3]
	v_mul_u32_u24_e32 v2, 0xb00, v9
	v_lshlrev_b32_e32 v2, 1, v2
	v_lshl_add_u64 v[4:5], v[10:11], 0, v[2:3]
	global_load_dwordx4 v[114:117], v[6:7], off
	global_load_dwordx4 v[118:121], v[6:7], off offset:128
	global_load_dwordx4 v[122:125], v[4:5], off
	global_load_dwordx4 v[126:129], v[4:5], off offset:128
	global_load_dwordx4 v[130:133], v[6:7], off offset:256
	global_load_dwordx4 v[134:137], v[6:7], off offset:384
	global_load_dwordx4 v[138:141], v[4:5], off offset:256
	global_load_dwordx4 v[142:145], v[4:5], off offset:384
	global_load_dwordx4 v[146:149], v[6:7], off offset:512
	global_load_dwordx4 v[150:153], v[6:7], off offset:640
	global_load_dwordx4 v[154:157], v[4:5], off offset:512
	global_load_dwordx4 v[158:161], v[4:5], off offset:640
	global_load_dwordx4 v[164:167], v[6:7], off offset:768
	global_load_dwordx4 v[168:171], v[6:7], off offset:896
	global_load_dwordx4 v[172:175], v[4:5], off offset:768
	global_load_dwordx4 v[176:179], v[4:5], off offset:896
	global_load_dwordx4 v[180:183], v[6:7], off offset:1024
	global_load_dwordx4 v[184:187], v[6:7], off offset:1152
	global_load_dwordx4 v[188:191], v[4:5], off offset:1024
	global_load_dwordx4 v[192:195], v[4:5], off offset:1152
	global_load_dwordx4 v[196:199], v[6:7], off offset:1280
	global_load_dwordx4 v[206:209], v[6:7], off offset:1408
	global_load_dwordx4 v[210:213], v[4:5], off offset:1280
	global_load_dwordx4 v[214:217], v[4:5], off offset:1408
	global_load_dwordx4 v[218:221], v[6:7], off offset:1536
	global_load_dwordx4 v[222:225], v[6:7], off offset:1664
	global_load_dwordx4 v[226:229], v[4:5], off offset:1536
	global_load_dwordx4 v[230:233], v[4:5], off offset:1664
	global_load_dwordx4 v[234:237], v[6:7], off offset:1792
	global_load_dwordx4 v[238:241], v[6:7], off offset:1920
	global_load_dwordx4 v[242:245], v[4:5], off offset:1792
	global_load_dwordx4 v[246:249], v[4:5], off offset:1920
	v_and_b32_e32 v2, 16, v203
	v_lshlrev_b32_e32 v110, 4, v1
	s_movk_i32 s3, 0x110
	v_or_b32_e32 v9, v2, v202
	v_mad_u32_u24 v9, v9, s3, v110
	v_add3_u32 v111, v163, v202, 64
	v_readlane_b32 s4, v251, 46
	v_readlane_b32 s5, v251, 47
	v_readlane_b32 s36, v251, 5
	v_readlane_b32 s38, v251, 7
	v_readlane_b32 s39, v251, 8
	v_readlane_b32 s40, v251, 9
	v_readlane_b32 s41, v251, 10
	v_readlane_b32 s37, v251, 6
	v_readlane_b32 s42, v251, 11
	v_readlane_b32 s43, v251, 12
	v_readlane_b32 s44, v251, 13
	v_readlane_b32 s45, v251, 14
	v_readlane_b32 s46, v251, 15
	v_readlane_b32 s47, v251, 16
	v_readlane_b32 s48, v251, 17
	v_readlane_b32 s49, v251, 18
	v_readlane_b32 s50, v251, 19
	v_readlane_b32 s51, v251, 20
	s_waitcnt vmcnt(31)
	ds_write_b128 v8, v[114:117]
	s_waitcnt vmcnt(30)
	ds_write_b128 v8, v[118:121] offset:128
	s_waitcnt vmcnt(29)
	ds_write_b128 v8, v[122:125] offset:34816
	s_waitcnt vmcnt(28)
	ds_write_b128 v8, v[126:129] offset:34944
	s_waitcnt lgkmcnt(0)
	s_barrier
	ds_read_b128 v[12:15], v9 offset:34816
	v_or_b32_e32 v10, v163, v202
	v_mad_u32_u24 v11, v10, s3, v110
	ds_read_b128 v[16:19], v11
	ds_read_b128 v[20:23], v9 offset:43520
	ds_read_b128 v[74:77], v11 offset:64
	ds_read_b128 v[78:81], v9 offset:34880
	s_waitcnt lgkmcnt(3)
	v_mfma_f32_16x16x32_bf16 v[12:15], v[12:15], v[16:19], 0
	global_load_dwordx4 v[114:117], v[6:7], off offset:2048
	global_load_dwordx4 v[118:121], v[6:7], off offset:2176
	ds_read_b128 v[90:93], v9 offset:43584
	s_waitcnt lgkmcnt(3)
	v_mfma_f32_16x16x32_bf16 v[16:19], v[20:23], v[16:19], 0
	global_load_dwordx4 v[122:125], v[4:5], off offset:2048
	global_load_dwordx4 v[126:129], v[4:5], off offset:2176
	ds_read_b128 v[98:101], v9 offset:34944
	s_waitcnt lgkmcnt(2)
	v_mfma_f32_16x16x32_bf16 v[12:15], v[78:81], v[74:77], v[12:15]
	ds_read_b128 v[78:81], v9 offset:43648
	ds_read_b128 v[102:105], v11 offset:128
	ds_read_b128 v[106:109], v11 offset:192
	s_waitcnt lgkmcnt(4)
	v_mfma_f32_16x16x32_bf16 v[16:19], v[90:93], v[74:77], v[16:19]
	ds_read_b128 v[74:77], v9 offset:35008
	ds_read_b128 v[90:93], v9 offset:43712
	s_waitcnt vmcnt(31)
	ds_write_b128 v8, v[130:133] offset:17408
	s_waitcnt vmcnt(30)
	ds_write_b128 v8, v[134:137] offset:17536
	s_waitcnt vmcnt(29)
	ds_write_b128 v8, v[138:141] offset:52224
	s_waitcnt vmcnt(28)
	ds_write_b128 v8, v[142:145] offset:52352
	s_waitcnt lgkmcnt(0)
	s_barrier
	ds_read_b128 v[28:31], v9 offset:52224
	ds_read_b128 v[32:35], v9 offset:60928
	v_mfma_f32_16x16x32_bf16 v[12:15], v[98:101], v[102:105], v[12:15]
	v_mfma_f32_16x16x32_bf16 v[16:19], v[78:81], v[102:105], v[16:19]
	v_mfma_f32_16x16x32_bf16 v[24:27], v[74:77], v[106:109], v[12:15]
	s_nop 5
	v_mad_u32_u24 v12, v111, s3, v110
	v_mfma_f32_16x16x32_bf16 v[14:17], v[90:93], v[106:109], v[16:19]
	ds_read_b128 v[36:39], v12
	ds_read_b128 v[74:77], v12 offset:64
	ds_read_b128 v[78:81], v9 offset:52288
	s_movk_i32 s3, 0x1000
	s_waitcnt lgkmcnt(2)
	v_mfma_f32_16x16x32_bf16 v[24:27], v[28:31], v[36:39], v[24:27]
	global_load_dwordx4 v[130:133], v[6:7], off offset:2304
	global_load_dwordx4 v[134:137], v[6:7], off offset:2432
	ds_read_b128 v[98:101], v9 offset:60992
	v_mfma_f32_16x16x32_bf16 v[14:17], v[32:35], v[36:39], v[14:17]
	global_load_dwordx4 v[138:141], v[4:5], off offset:2304
	global_load_dwordx4 v[142:145], v[4:5], off offset:2432
	ds_read_b128 v[102:105], v9 offset:52352
	s_waitcnt lgkmcnt(2)
	v_mfma_f32_16x16x32_bf16 v[24:27], v[78:81], v[74:77], v[24:27]
	ds_read_b128 v[78:81], v9 offset:61056
	ds_read_b128 v[106:109], v12 offset:128
	ds_read_b128 v[110:113], v12 offset:192
	s_waitcnt lgkmcnt(4)
	v_mfma_f32_16x16x32_bf16 v[14:17], v[98:101], v[74:77], v[14:17]
	ds_read_b128 v[74:77], v9 offset:52416
	ds_read_b128 v[98:101], v9 offset:61120
	s_waitcnt vmcnt(31)
	ds_write_b128 v8, v[146:149]
	s_waitcnt vmcnt(30)
	ds_write_b128 v8, v[150:153] offset:128
	s_waitcnt vmcnt(29)
	ds_write_b128 v8, v[154:157] offset:34816
	s_waitcnt vmcnt(28)
	ds_write_b128 v8, v[158:161] offset:34944
	s_waitcnt lgkmcnt(0)
	s_barrier
	ds_read_b128 v[40:43], v9 offset:34816
	v_mfma_f32_16x16x32_bf16 v[24:27], v[102:105], v[106:109], v[24:27]
	ds_read_b128 v[44:47], v11
	ds_read_b128 v[48:51], v11 offset:64
	ds_read_b128 v[52:55], v9 offset:34880
	v_mfma_f32_16x16x32_bf16 v[14:17], v[78:81], v[106:109], v[14:17]
	v_mfma_f32_16x16x32_bf16 v[24:27], v[74:77], v[110:113], v[24:27]
	v_mfma_f32_16x16x32_bf16 v[14:17], v[98:101], v[110:113], v[14:17]
	s_waitcnt lgkmcnt(2)
	v_mfma_f32_16x16x32_bf16 v[24:27], v[40:43], v[44:47], v[24:27]
	ds_read_b128 v[40:43], v9 offset:43520
	ds_read_b128 v[74:77], v9 offset:43584
	s_waitcnt lgkmcnt(1)
	v_mfma_f32_16x16x32_bf16 v[14:17], v[40:43], v[44:47], v[14:17]
	v_mfma_f32_16x16x32_bf16 v[24:27], v[52:55], v[48:51], v[24:27]
	ds_read_b128 v[40:43], v9 offset:34944
	ds_read_b128 v[44:47], v11 offset:128
	ds_read_b128 v[52:55], v9 offset:43648
	s_waitcnt lgkmcnt(3)
	v_mfma_f32_16x16x32_bf16 v[14:17], v[74:77], v[48:51], v[14:17]
	global_load_dwordx4 v[146:149], v[6:7], off offset:2560
	global_load_dwordx4 v[150:153], v[6:7], off offset:2688
	ds_read_b128 v[78:81], v11 offset:192
	ds_read_b128 v[98:101], v9 offset:35008
	s_waitcnt lgkmcnt(3)
	v_mfma_f32_16x16x32_bf16 v[24:27], v[40:43], v[44:47], v[24:27]
	global_load_dwordx4 v[154:157], v[4:5], off offset:2560
	global_load_dwordx4 v[158:161], v[4:5], off offset:2688
	ds_read_b128 v[106:109], v9 offset:43712
	s_waitcnt vmcnt(31)
	ds_write_b128 v8, v[164:167] offset:17408
	s_waitcnt vmcnt(30)
	ds_write_b128 v8, v[168:171] offset:17536
	s_waitcnt vmcnt(29)
	ds_write_b128 v8, v[172:175] offset:52224
	s_waitcnt lgkmcnt(6)
	v_mfma_f32_16x16x32_bf16 v[14:17], v[52:55], v[44:47], v[14:17]
	s_waitcnt vmcnt(28)
	ds_write_b128 v8, v[176:179] offset:52352
	s_waitcnt lgkmcnt(0)
	s_barrier
	ds_read_b128 v[44:47], v9 offset:52224
	v_mfma_f32_16x16x32_bf16 v[24:27], v[98:101], v[78:81], v[24:27]
	ds_read_b128 v[52:55], v12
	ds_read_b128 v[56:59], v12 offset:64
	ds_read_b128 v[60:63], v9 offset:52288
	v_mfma_f32_16x16x32_bf16 v[14:17], v[106:109], v[78:81], v[14:17]
	s_waitcnt lgkmcnt(2)
	v_mfma_f32_16x16x32_bf16 v[24:27], v[44:47], v[52:55], v[24:27]
	ds_read_b128 v[44:47], v9 offset:60928
	ds_read_b128 v[64:67], v9 offset:60992
	s_waitcnt lgkmcnt(1)
	v_mfma_f32_16x16x32_bf16 v[14:17], v[44:47], v[52:55], v[14:17]
	ds_read_b128 v[44:47], v9 offset:52352
	v_mfma_f32_16x16x32_bf16 v[24:27], v[60:63], v[56:59], v[24:27]
	s_waitcnt lgkmcnt(1)
	v_mfma_f32_16x16x32_bf16 v[14:17], v[64:67], v[56:59], v[14:17]
	ds_read_b128 v[52:55], v12 offset:128
	ds_read_b128 v[56:59], v12 offset:192
	ds_read_b128 v[60:63], v9 offset:52416
	s_waitcnt lgkmcnt(2)
	v_mfma_f32_16x16x32_bf16 v[24:27], v[44:47], v[52:55], v[24:27]
	ds_read_b128 v[44:47], v9 offset:61056
	ds_read_b128 v[64:67], v9 offset:61120
	s_waitcnt lgkmcnt(1)
	v_mfma_f32_16x16x32_bf16 v[14:17], v[44:47], v[52:55], v[14:17]
	global_load_dwordx4 v[164:167], v[6:7], off offset:2816
	global_load_dwordx4 v[168:171], v[6:7], off offset:2944
	global_load_dwordx4 v[172:175], v[4:5], off offset:2816
	global_load_dwordx4 v[176:179], v[4:5], off offset:2944
	s_waitcnt vmcnt(31)
	ds_write_b128 v8, v[180:183]
	s_waitcnt vmcnt(30)
	ds_write_b128 v8, v[184:187] offset:128
	s_waitcnt vmcnt(29)
	ds_write_b128 v8, v[188:191] offset:34816
	s_waitcnt vmcnt(28)
	ds_write_b128 v8, v[192:195] offset:34944
	s_waitcnt lgkmcnt(0)
	s_barrier
	ds_read_b128 v[18:21], v9 offset:34816
	v_mfma_f32_16x16x32_bf16 v[24:27], v[60:63], v[56:59], v[24:27]
	v_mfma_f32_16x16x32_bf16 v[14:17], v[64:67], v[56:59], v[14:17]
	ds_read_b128 v[56:59], v11
	ds_read_b128 v[60:63], v11 offset:64
	ds_read_b128 v[64:67], v9 offset:34880
	s_waitcnt lgkmcnt(2)
	v_mfma_f32_16x16x32_bf16 v[18:21], v[18:21], v[56:59], v[24:27]
	s_nop 2
	ds_read_b128 v[22:25], v9 offset:43520
	ds_read_b128 v[82:85], v9 offset:43584
	s_waitcnt lgkmcnt(1)
	v_mfma_f32_16x16x32_bf16 v[14:17], v[22:25], v[56:59], v[14:17]
	ds_read_b128 v[22:25], v9 offset:34944
	v_mfma_f32_16x16x32_bf16 v[18:21], v[64:67], v[60:63], v[18:21]
	s_waitcnt lgkmcnt(1)
	v_mfma_f32_16x16x32_bf16 v[14:17], v[82:85], v[60:63], v[14:17]
	ds_read_b128 v[56:59], v11 offset:128
	ds_read_b128 v[60:63], v11 offset:192
	ds_read_b128 v[64:67], v9 offset:35008
	s_waitcnt lgkmcnt(2)
	v_mfma_f32_16x16x32_bf16 v[18:21], v[22:25], v[56:59], v[18:21]
	ds_read_b128 v[22:25], v9 offset:43648
	ds_read_b128 v[82:85], v9 offset:43712
	s_waitcnt lgkmcnt(1)
	v_mfma_f32_16x16x32_bf16 v[14:17], v[22:25], v[56:59], v[14:17]
	global_load_dwordx4 v[180:183], v[6:7], off offset:3072
	global_load_dwordx4 v[184:187], v[6:7], off offset:3200
	global_load_dwordx4 v[188:191], v[4:5], off offset:3072
	global_load_dwordx4 v[192:195], v[4:5], off offset:3200
	s_waitcnt vmcnt(31)
	ds_write_b128 v8, v[196:199] offset:17408
	s_waitcnt vmcnt(30)
	ds_write_b128 v8, v[206:209] offset:17536
	s_waitcnt vmcnt(29)
	ds_write_b128 v8, v[210:213] offset:52224
	s_waitcnt vmcnt(28)
	ds_write_b128 v8, v[214:217] offset:52352
	s_waitcnt lgkmcnt(0)
	s_barrier
	ds_read_b128 v[26:29], v9 offset:52224
	v_mfma_f32_16x16x32_bf16 v[18:21], v[64:67], v[60:63], v[18:21]
	v_mfma_f32_16x16x32_bf16 v[14:17], v[82:85], v[60:63], v[14:17]
	ds_read_b128 v[30:33], v12
	ds_read_b128 v[34:37], v12 offset:64
	ds_read_b128 v[60:63], v9 offset:52288
	s_waitcnt lgkmcnt(2)
	v_mfma_f32_16x16x32_bf16 v[18:21], v[26:29], v[30:33], v[18:21]
	ds_read_b128 v[26:29], v9 offset:60928
	ds_read_b128 v[64:67], v9 offset:60992
	s_waitcnt lgkmcnt(1)
	v_mfma_f32_16x16x32_bf16 v[14:17], v[26:29], v[30:33], v[14:17]
	ds_read_b128 v[26:29], v9 offset:52352
	v_mfma_f32_16x16x32_bf16 v[18:21], v[60:63], v[34:37], v[18:21]
	s_waitcnt lgkmcnt(1)
	v_mfma_f32_16x16x32_bf16 v[14:17], v[64:67], v[34:37], v[14:17]
	ds_read_b128 v[30:33], v12 offset:128
	ds_read_b128 v[34:37], v12 offset:192
	ds_read_b128 v[60:63], v9 offset:52416
	s_waitcnt lgkmcnt(2)
	v_mfma_f32_16x16x32_bf16 v[18:21], v[26:29], v[30:33], v[18:21]
	ds_read_b128 v[26:29], v9 offset:61056
	ds_read_b128 v[64:67], v9 offset:61120
	s_waitcnt lgkmcnt(1)
	v_mfma_f32_16x16x32_bf16 v[14:17], v[26:29], v[30:33], v[14:17]
	global_load_dwordx4 v[196:199], v[6:7], off offset:3328
	global_load_dwordx4 v[206:209], v[6:7], off offset:3456
	global_load_dwordx4 v[210:213], v[4:5], off offset:3328
	global_load_dwordx4 v[214:217], v[4:5], off offset:3456
	s_waitcnt vmcnt(31)
	ds_write_b128 v8, v[218:221]
	s_waitcnt vmcnt(30)
	ds_write_b128 v8, v[222:225] offset:128
	s_waitcnt vmcnt(29)
	ds_write_b128 v8, v[226:229] offset:34816
	s_waitcnt vmcnt(28)
	ds_write_b128 v8, v[230:233] offset:34944
	s_waitcnt lgkmcnt(0)
	s_barrier
	ds_read_b128 v[38:41], v9 offset:34816
	v_mfma_f32_16x16x32_bf16 v[18:21], v[60:63], v[34:37], v[18:21]
	v_add_co_u32_e32 v102, vcc, s3, v6
	v_mfma_f32_16x16x32_bf16 v[14:17], v[64:67], v[34:37], v[14:17]
	ds_read_b128 v[34:37], v11
	ds_read_b128 v[48:51], v11 offset:64
	ds_read_b128 v[60:63], v9 offset:34880
	v_addc_co_u32_e32 v103, vcc, 0, v7, vcc
	s_waitcnt lgkmcnt(2)
	v_mfma_f32_16x16x32_bf16 v[18:21], v[38:41], v[34:37], v[18:21]
	ds_read_b128 v[38:41], v9 offset:43520
	ds_read_b128 v[64:67], v9 offset:43584
	v_add_co_u32_e32 v104, vcc, s3, v4
	s_waitcnt lgkmcnt(1)
	v_mfma_f32_16x16x32_bf16 v[14:17], v[38:41], v[34:37], v[14:17]
	ds_read_b128 v[34:37], v9 offset:34944
	v_addc_co_u32_e32 v105, vcc, 0, v5, vcc
	v_mfma_f32_16x16x32_bf16 v[18:21], v[60:63], v[48:51], v[18:21]
	s_waitcnt lgkmcnt(1)
	v_mfma_f32_16x16x32_bf16 v[14:17], v[64:67], v[48:51], v[14:17]
	ds_read_b128 v[38:41], v11 offset:128
	ds_read_b128 v[48:51], v11 offset:192
	ds_read_b128 v[60:63], v9 offset:35008
	s_waitcnt lgkmcnt(2)
	v_mfma_f32_16x16x32_bf16 v[18:21], v[34:37], v[38:41], v[18:21]
	ds_read_b128 v[34:37], v9 offset:43648
	ds_read_b128 v[64:67], v9 offset:43712
	s_waitcnt lgkmcnt(1)
	v_mfma_f32_16x16x32_bf16 v[14:17], v[34:37], v[38:41], v[14:17]
	global_load_dwordx4 v[218:221], v[6:7], off offset:3584
	global_load_dwordx4 v[222:225], v[6:7], off offset:3712
	global_load_dwordx4 v[226:229], v[4:5], off offset:3584
	global_load_dwordx4 v[230:233], v[4:5], off offset:3712
	s_waitcnt vmcnt(31)
	ds_write_b128 v8, v[234:237] offset:17408
	s_waitcnt vmcnt(30)
	ds_write_b128 v8, v[238:241] offset:17536
	s_waitcnt vmcnt(29)
	ds_write_b128 v8, v[242:245] offset:52224
	s_waitcnt vmcnt(28)
	ds_write_b128 v8, v[246:249] offset:52352
	s_waitcnt lgkmcnt(0)
	s_barrier
	ds_read_b128 v[42:45], v9 offset:52224
	v_mfma_f32_16x16x32_bf16 v[18:21], v[60:63], v[48:51], v[18:21]
	v_mfma_f32_16x16x32_bf16 v[14:17], v[64:67], v[48:51], v[14:17]
	ds_read_b128 v[46:49], v12
	ds_read_b128 v[50:53], v12 offset:64
	ds_read_b128 v[60:63], v9 offset:52288
	s_waitcnt lgkmcnt(2)
	v_mfma_f32_16x16x32_bf16 v[18:21], v[42:45], v[46:49], v[18:21]
	ds_read_b128 v[42:45], v9 offset:60928
	ds_read_b128 v[64:67], v9 offset:60992
	s_waitcnt lgkmcnt(1)
	v_mfma_f32_16x16x32_bf16 v[14:17], v[42:45], v[46:49], v[14:17]
	ds_read_b128 v[42:45], v9 offset:52352
	v_mfma_f32_16x16x32_bf16 v[18:21], v[60:63], v[50:53], v[18:21]
	s_waitcnt lgkmcnt(1)
	v_mfma_f32_16x16x32_bf16 v[14:17], v[64:67], v[50:53], v[14:17]
	ds_read_b128 v[46:49], v12 offset:128
	ds_read_b128 v[50:53], v12 offset:192
	ds_read_b128 v[60:63], v9 offset:52416
	s_waitcnt lgkmcnt(2)
	v_mfma_f32_16x16x32_bf16 v[18:21], v[42:45], v[46:49], v[18:21]
	ds_read_b128 v[42:45], v9 offset:61056
	ds_read_b128 v[64:67], v9 offset:61120
	s_waitcnt lgkmcnt(1)
	v_mfma_f32_16x16x32_bf16 v[14:17], v[42:45], v[46:49], v[14:17]
	global_load_dwordx4 v[234:237], v[6:7], off offset:3840
	global_load_dwordx4 v[238:241], v[6:7], off offset:3968
	global_load_dwordx4 v[242:245], v[4:5], off offset:3840
	global_load_dwordx4 v[246:249], v[4:5], off offset:3968
	s_waitcnt vmcnt(31)
	ds_write_b128 v8, v[114:117]
	s_waitcnt vmcnt(30)
	ds_write_b128 v8, v[118:121] offset:128
	s_waitcnt vmcnt(29)
	ds_write_b128 v8, v[122:125] offset:34816
	s_waitcnt vmcnt(28)
	ds_write_b128 v8, v[126:129] offset:34944
	s_waitcnt lgkmcnt(0)
	s_barrier
	ds_read_b128 v[22:25], v9 offset:34816
	v_mfma_f32_16x16x32_bf16 v[18:21], v[60:63], v[50:53], v[18:21]
	v_mfma_f32_16x16x32_bf16 v[14:17], v[64:67], v[50:53], v[14:17]
	ds_read_b128 v[50:53], v11
	ds_read_b128 v[54:57], v11 offset:64
	ds_read_b128 v[58:61], v9 offset:34880
	s_waitcnt lgkmcnt(2)
	v_mfma_f32_16x16x32_bf16 v[18:21], v[22:25], v[50:53], v[18:21]
	ds_read_b128 v[22:25], v9 offset:43520
	ds_read_b128 v[62:65], v9 offset:43584
	s_waitcnt lgkmcnt(1)
	v_mfma_f32_16x16x32_bf16 v[14:17], v[22:25], v[50:53], v[14:17]
	ds_read_b128 v[22:25], v9 offset:34944
	v_mfma_f32_16x16x32_bf16 v[18:21], v[58:61], v[54:57], v[18:21]
	s_waitcnt lgkmcnt(1)
	v_mfma_f32_16x16x32_bf16 v[14:17], v[62:65], v[54:57], v[14:17]
	ds_read_b128 v[50:53], v11 offset:128
	ds_read_b128 v[54:57], v11 offset:192
	ds_read_b128 v[58:61], v9 offset:35008
	s_waitcnt lgkmcnt(2)
	v_mfma_f32_16x16x32_bf16 v[18:21], v[22:25], v[50:53], v[18:21]
	ds_read_b128 v[22:25], v9 offset:43648
	ds_read_b128 v[62:65], v9 offset:43712
	s_waitcnt lgkmcnt(1)
	v_mfma_f32_16x16x32_bf16 v[14:17], v[22:25], v[50:53], v[14:17]
	global_load_dwordx4 v[114:117], v[102:103], off
	global_load_dwordx4 v[118:121], v[102:103], off offset:128
	global_load_dwordx4 v[122:125], v[104:105], off
	global_load_dwordx4 v[126:129], v[104:105], off offset:128
	s_waitcnt vmcnt(31)
	ds_write_b128 v8, v[130:133] offset:17408
	s_waitcnt vmcnt(30)
	ds_write_b128 v8, v[134:137] offset:17536
	s_waitcnt vmcnt(29)
	ds_write_b128 v8, v[138:141] offset:52224
	s_waitcnt vmcnt(28)
	ds_write_b128 v8, v[142:145] offset:52352
	s_waitcnt lgkmcnt(0)
	s_barrier
	ds_read_b128 v[26:29], v9 offset:52224
	v_mfma_f32_16x16x32_bf16 v[18:21], v[58:61], v[54:57], v[18:21]
	v_mfma_f32_16x16x32_bf16 v[14:17], v[62:65], v[54:57], v[14:17]
	ds_read_b128 v[30:33], v12
	ds_read_b128 v[54:57], v12 offset:64
	ds_read_b128 v[58:61], v9 offset:52288
	s_waitcnt lgkmcnt(2)
	v_mfma_f32_16x16x32_bf16 v[18:21], v[26:29], v[30:33], v[18:21]
	ds_read_b128 v[26:29], v9 offset:60928
	ds_read_b128 v[62:65], v9 offset:60992
	s_waitcnt lgkmcnt(1)
	v_mfma_f32_16x16x32_bf16 v[14:17], v[26:29], v[30:33], v[14:17]
	ds_read_b128 v[26:29], v9 offset:52352
	v_mfma_f32_16x16x32_bf16 v[18:21], v[58:61], v[54:57], v[18:21]
	s_waitcnt lgkmcnt(1)
	v_mfma_f32_16x16x32_bf16 v[14:17], v[62:65], v[54:57], v[14:17]
	ds_read_b128 v[30:33], v12 offset:128
	ds_read_b128 v[54:57], v12 offset:192
	ds_read_b128 v[58:61], v9 offset:52416
	s_waitcnt lgkmcnt(2)
	v_mfma_f32_16x16x32_bf16 v[18:21], v[26:29], v[30:33], v[18:21]
	ds_read_b128 v[26:29], v9 offset:61056
	ds_read_b128 v[62:65], v9 offset:61120
	s_waitcnt lgkmcnt(1)
	v_mfma_f32_16x16x32_bf16 v[14:17], v[26:29], v[30:33], v[14:17]
	global_load_dwordx4 v[130:133], v[102:103], off offset:256
	global_load_dwordx4 v[134:137], v[102:103], off offset:384
	global_load_dwordx4 v[138:141], v[104:105], off offset:256
	global_load_dwordx4 v[142:145], v[104:105], off offset:384
	s_waitcnt vmcnt(31)
	ds_write_b128 v8, v[146:149]
	s_waitcnt vmcnt(30)
	ds_write_b128 v8, v[150:153] offset:128
	s_waitcnt vmcnt(29)
	ds_write_b128 v8, v[154:157] offset:34816
	s_waitcnt vmcnt(28)
	ds_write_b128 v8, v[158:161] offset:34944
	s_waitcnt lgkmcnt(0)
	s_barrier
	ds_read_b128 v[34:37], v9 offset:34816
	v_mfma_f32_16x16x32_bf16 v[18:21], v[58:61], v[54:57], v[18:21]
	v_mfma_f32_16x16x32_bf16 v[14:17], v[62:65], v[54:57], v[14:17]
	ds_read_b128 v[38:41], v11
	ds_read_b128 v[54:57], v11 offset:64
	ds_read_b128 v[58:61], v9 offset:34880
	s_waitcnt lgkmcnt(2)
	v_mfma_f32_16x16x32_bf16 v[18:21], v[34:37], v[38:41], v[18:21]
	ds_read_b128 v[34:37], v9 offset:43520
	ds_read_b128 v[62:65], v9 offset:43584
	s_waitcnt lgkmcnt(1)
	v_mfma_f32_16x16x32_bf16 v[14:17], v[34:37], v[38:41], v[14:17]
	ds_read_b128 v[34:37], v9 offset:34944
	v_mfma_f32_16x16x32_bf16 v[18:21], v[58:61], v[54:57], v[18:21]
	s_waitcnt lgkmcnt(1)
	v_mfma_f32_16x16x32_bf16 v[14:17], v[62:65], v[54:57], v[14:17]
	ds_read_b128 v[38:41], v11 offset:128
	ds_read_b128 v[54:57], v11 offset:192
	ds_read_b128 v[58:61], v9 offset:35008
	s_waitcnt lgkmcnt(2)
	v_mfma_f32_16x16x32_bf16 v[18:21], v[34:37], v[38:41], v[18:21]
	ds_read_b128 v[34:37], v9 offset:43648
	ds_read_b128 v[62:65], v9 offset:43712
	s_waitcnt lgkmcnt(1)
	v_mfma_f32_16x16x32_bf16 v[14:17], v[34:37], v[38:41], v[14:17]
	global_load_dwordx4 v[146:149], v[102:103], off offset:512
	global_load_dwordx4 v[150:153], v[102:103], off offset:640
	global_load_dwordx4 v[154:157], v[104:105], off offset:512
	global_load_dwordx4 v[158:161], v[104:105], off offset:640
	s_waitcnt vmcnt(31)
	ds_write_b128 v8, v[164:167] offset:17408
	s_waitcnt vmcnt(30)
	ds_write_b128 v8, v[168:171] offset:17536
	s_waitcnt vmcnt(29)
	ds_write_b128 v8, v[172:175] offset:52224
	s_waitcnt vmcnt(28)
	ds_write_b128 v8, v[176:179] offset:52352
	s_waitcnt lgkmcnt(0)
	s_barrier
	ds_read_b128 v[42:45], v9 offset:52224
	v_mfma_f32_16x16x32_bf16 v[18:21], v[58:61], v[54:57], v[18:21]
	v_mfma_f32_16x16x32_bf16 v[14:17], v[62:65], v[54:57], v[14:17]
	ds_read_b128 v[46:49], v12
	ds_read_b128 v[54:57], v12 offset:64
	ds_read_b128 v[58:61], v9 offset:52288
	s_waitcnt lgkmcnt(2)
	v_mfma_f32_16x16x32_bf16 v[18:21], v[42:45], v[46:49], v[18:21]
	ds_read_b128 v[42:45], v9 offset:60928
	ds_read_b128 v[62:65], v9 offset:60992
	s_waitcnt lgkmcnt(1)
	v_mfma_f32_16x16x32_bf16 v[14:17], v[42:45], v[46:49], v[14:17]
	ds_read_b128 v[42:45], v9 offset:52352
	v_mfma_f32_16x16x32_bf16 v[18:21], v[58:61], v[54:57], v[18:21]
	s_waitcnt lgkmcnt(1)
	v_mfma_f32_16x16x32_bf16 v[14:17], v[62:65], v[54:57], v[14:17]
	ds_read_b128 v[46:49], v12 offset:128
	ds_read_b128 v[54:57], v12 offset:192
	ds_read_b128 v[58:61], v9 offset:52416
	s_waitcnt lgkmcnt(2)
	v_mfma_f32_16x16x32_bf16 v[18:21], v[42:45], v[46:49], v[18:21]
	ds_read_b128 v[42:45], v9 offset:61056
	ds_read_b128 v[62:65], v9 offset:61120
	s_waitcnt lgkmcnt(1)
	v_mfma_f32_16x16x32_bf16 v[14:17], v[42:45], v[46:49], v[14:17]
	global_load_dwordx4 v[164:167], v[102:103], off offset:768
	global_load_dwordx4 v[168:171], v[102:103], off offset:896
	global_load_dwordx4 v[172:175], v[104:105], off offset:768
	global_load_dwordx4 v[176:179], v[104:105], off offset:896
	s_waitcnt vmcnt(31)
	ds_write_b128 v8, v[180:183]
	s_waitcnt vmcnt(30)
	ds_write_b128 v8, v[184:187] offset:128
	s_waitcnt vmcnt(29)
	ds_write_b128 v8, v[188:191] offset:34816
	s_waitcnt vmcnt(28)
	ds_write_b128 v8, v[192:195] offset:34944
	s_waitcnt lgkmcnt(0)
	s_barrier
	ds_read_b128 v[22:25], v9 offset:34816
	v_mfma_f32_16x16x32_bf16 v[18:21], v[58:61], v[54:57], v[18:21]
	v_mfma_f32_16x16x32_bf16 v[14:17], v[62:65], v[54:57], v[14:17]
	ds_read_b128 v[50:53], v11
	ds_read_b128 v[54:57], v11 offset:64
	ds_read_b128 v[58:61], v9 offset:34880
	s_waitcnt lgkmcnt(2)
	v_mfma_f32_16x16x32_bf16 v[18:21], v[22:25], v[50:53], v[18:21]
	ds_read_b128 v[22:25], v9 offset:43520
	ds_read_b128 v[62:65], v9 offset:43584
	s_waitcnt lgkmcnt(1)
	v_mfma_f32_16x16x32_bf16 v[14:17], v[22:25], v[50:53], v[14:17]
	v_mfma_f32_16x16x32_bf16 v[18:21], v[58:61], v[54:57], v[18:21]
	s_waitcnt lgkmcnt(0)
	v_mfma_f32_16x16x32_bf16 v[14:17], v[62:65], v[54:57], v[14:17]
	ds_read_b128 v[22:25], v9 offset:34944
	ds_read_b128 v[50:53], v11 offset:128
	ds_read_b128 v[54:57], v9 offset:43648
	ds_read_b128 v[58:61], v11 offset:192
	ds_read_b128 v[62:65], v9 offset:35008
	s_waitcnt lgkmcnt(3)
	v_mfma_f32_16x16x32_bf16 v[18:21], v[22:25], v[50:53], v[18:21]
	global_load_dwordx4 v[180:183], v[102:103], off offset:1024
	global_load_dwordx4 v[184:187], v[102:103], off offset:1152
	ds_read_b128 v[94:97], v9 offset:43712
	s_waitcnt lgkmcnt(3)
	v_mfma_f32_16x16x32_bf16 v[14:17], v[54:57], v[50:53], v[14:17]
	global_load_dwordx4 v[188:191], v[104:105], off offset:1024
	global_load_dwordx4 v[192:195], v[104:105], off offset:1152
	s_waitcnt vmcnt(31)
	ds_write_b128 v8, v[196:199] offset:17408
	s_waitcnt vmcnt(30)
	ds_write_b128 v8, v[206:209] offset:17536
	s_waitcnt vmcnt(29)
	ds_write_b128 v8, v[210:213] offset:52224
	s_waitcnt vmcnt(28)
	ds_write_b128 v8, v[214:217] offset:52352
	s_waitcnt lgkmcnt(0)
	s_barrier
	ds_read_b128 v[26:29], v9 offset:52224
	v_mfma_f32_16x16x32_bf16 v[18:21], v[62:65], v[58:61], v[18:21]
	v_mfma_f32_16x16x32_bf16 v[14:17], v[94:97], v[58:61], v[14:17]
	ds_read_b128 v[30:33], v12
	ds_read_b128 v[54:57], v12 offset:64
	ds_read_b128 v[58:61], v9 offset:52288
	s_waitcnt lgkmcnt(2)
	v_mfma_f32_16x16x32_bf16 v[18:21], v[26:29], v[30:33], v[18:21]
	ds_read_b128 v[26:29], v9 offset:60928
	ds_read_b128 v[62:65], v9 offset:60992
	s_waitcnt lgkmcnt(1)
	v_mfma_f32_16x16x32_bf16 v[14:17], v[26:29], v[30:33], v[14:17]
	ds_read_b128 v[26:29], v9 offset:52352
	v_mfma_f32_16x16x32_bf16 v[18:21], v[58:61], v[54:57], v[18:21]
	s_waitcnt lgkmcnt(1)
	v_mfma_f32_16x16x32_bf16 v[14:17], v[62:65], v[54:57], v[14:17]
	ds_read_b128 v[30:33], v12 offset:128
	ds_read_b128 v[54:57], v12 offset:192
	ds_read_b128 v[58:61], v9 offset:52416
	s_waitcnt lgkmcnt(2)
	v_mfma_f32_16x16x32_bf16 v[18:21], v[26:29], v[30:33], v[18:21]
	ds_read_b128 v[26:29], v9 offset:61056
	ds_read_b128 v[62:65], v9 offset:61120
	s_waitcnt lgkmcnt(1)
	v_mfma_f32_16x16x32_bf16 v[14:17], v[26:29], v[30:33], v[14:17]
	global_load_dwordx4 v[196:199], v[102:103], off offset:1280
	global_load_dwordx4 v[206:209], v[102:103], off offset:1408
	global_load_dwordx4 v[210:213], v[104:105], off offset:1280
	global_load_dwordx4 v[214:217], v[104:105], off offset:1408
	s_waitcnt vmcnt(31)
	ds_write_b128 v8, v[218:221]
	s_waitcnt vmcnt(30)
	ds_write_b128 v8, v[222:225] offset:128
	s_waitcnt vmcnt(29)
	ds_write_b128 v8, v[226:229] offset:34816
	s_waitcnt vmcnt(28)
	ds_write_b128 v8, v[230:233] offset:34944
	s_waitcnt lgkmcnt(0)
	s_barrier
	ds_read_b128 v[34:37], v9 offset:34816
	v_mfma_f32_16x16x32_bf16 v[18:21], v[58:61], v[54:57], v[18:21]
	v_mfma_f32_16x16x32_bf16 v[14:17], v[62:65], v[54:57], v[14:17]
	ds_read_b128 v[38:41], v11
	ds_read_b128 v[54:57], v11 offset:64
	ds_read_b128 v[58:61], v9 offset:34880
	s_waitcnt lgkmcnt(2)
	v_mfma_f32_16x16x32_bf16 v[18:21], v[34:37], v[38:41], v[18:21]
	ds_read_b128 v[34:37], v9 offset:43520
	ds_read_b128 v[62:65], v9 offset:43584
	s_waitcnt lgkmcnt(1)
	v_mfma_f32_16x16x32_bf16 v[14:17], v[34:37], v[38:41], v[14:17]
	ds_read_b128 v[34:37], v9 offset:34944
	v_mfma_f32_16x16x32_bf16 v[18:21], v[58:61], v[54:57], v[18:21]
	s_waitcnt lgkmcnt(1)
	v_mfma_f32_16x16x32_bf16 v[14:17], v[62:65], v[54:57], v[14:17]
	ds_read_b128 v[38:41], v11 offset:128
	ds_read_b128 v[54:57], v11 offset:192
	ds_read_b128 v[58:61], v9 offset:35008
	s_waitcnt lgkmcnt(2)
	v_mfma_f32_16x16x32_bf16 v[18:21], v[34:37], v[38:41], v[18:21]
	ds_read_b128 v[34:37], v9 offset:43648
	ds_read_b128 v[62:65], v9 offset:43712
	s_waitcnt lgkmcnt(1)
	v_mfma_f32_16x16x32_bf16 v[14:17], v[34:37], v[38:41], v[14:17]
	s_waitcnt vmcnt(27)
	ds_write_b128 v8, v[234:237] offset:17408
	s_waitcnt vmcnt(26)
	ds_write_b128 v8, v[238:241] offset:17536
	s_waitcnt vmcnt(25)
	ds_write_b128 v8, v[242:245] offset:52224
	s_waitcnt vmcnt(24)
	ds_write_b128 v8, v[246:249] offset:52352
	s_waitcnt lgkmcnt(0)
	s_barrier
	ds_read_b128 v[42:45], v9 offset:52224
	v_mfma_f32_16x16x32_bf16 v[18:21], v[58:61], v[54:57], v[18:21]
	v_mfma_f32_16x16x32_bf16 v[14:17], v[62:65], v[54:57], v[14:17]
	ds_read_b128 v[46:49], v12
	ds_read_b128 v[54:57], v12 offset:64
	ds_read_b128 v[58:61], v9 offset:52288
	s_waitcnt lgkmcnt(2)
	v_mfma_f32_16x16x32_bf16 v[18:21], v[42:45], v[46:49], v[18:21]
	ds_read_b128 v[42:45], v9 offset:60928
	ds_read_b128 v[62:65], v9 offset:60992
	s_waitcnt lgkmcnt(1)
	v_mfma_f32_16x16x32_bf16 v[14:17], v[42:45], v[46:49], v[14:17]
	ds_read_b128 v[42:45], v9 offset:52352
	v_mfma_f32_16x16x32_bf16 v[18:21], v[58:61], v[54:57], v[18:21]
	s_waitcnt lgkmcnt(1)
	v_mfma_f32_16x16x32_bf16 v[14:17], v[62:65], v[54:57], v[14:17]
	ds_read_b128 v[46:49], v12 offset:128
	ds_read_b128 v[54:57], v12 offset:192
	ds_read_b128 v[58:61], v9 offset:52416
	s_waitcnt lgkmcnt(2)
	v_mfma_f32_16x16x32_bf16 v[18:21], v[42:45], v[46:49], v[18:21]
	ds_read_b128 v[42:45], v9 offset:61056
	ds_read_b128 v[62:65], v9 offset:61120
	s_waitcnt lgkmcnt(1)
	v_mfma_f32_16x16x32_bf16 v[14:17], v[42:45], v[46:49], v[14:17]
	s_waitcnt vmcnt(23)
	ds_write_b128 v8, v[114:117]
	s_waitcnt vmcnt(22)
	ds_write_b128 v8, v[118:121] offset:128
	s_waitcnt vmcnt(21)
	ds_write_b128 v8, v[122:125] offset:34816
	s_waitcnt vmcnt(20)
	ds_write_b128 v8, v[126:129] offset:34944
	s_waitcnt lgkmcnt(0)
	s_barrier
	ds_read_b128 v[4:7], v9 offset:34816
	v_mfma_f32_16x16x32_bf16 v[18:21], v[58:61], v[54:57], v[18:21]
	v_mfma_f32_16x16x32_bf16 v[14:17], v[62:65], v[54:57], v[14:17]
	ds_read_b128 v[22:25], v11
	ds_read_b128 v[50:53], v11 offset:64
	ds_read_b128 v[54:57], v9 offset:34880
	s_waitcnt lgkmcnt(2)
	v_mfma_f32_16x16x32_bf16 v[4:7], v[4:7], v[22:25], v[18:21]
	s_nop 2
	ds_read_b128 v[18:21], v9 offset:43520
	ds_read_b128 v[58:61], v9 offset:43584
	s_waitcnt lgkmcnt(1)
	v_mfma_f32_16x16x32_bf16 v[14:17], v[18:21], v[22:25], v[14:17]
	ds_read_b128 v[18:21], v9 offset:34944
	v_mfma_f32_16x16x32_bf16 v[4:7], v[54:57], v[50:53], v[4:7]
	s_waitcnt lgkmcnt(1)
	v_mfma_f32_16x16x32_bf16 v[14:17], v[58:61], v[50:53], v[14:17]
	ds_read_b128 v[22:25], v11 offset:128
	ds_read_b128 v[50:53], v11 offset:192
	ds_read_b128 v[54:57], v9 offset:35008
	s_waitcnt lgkmcnt(2)
	v_mfma_f32_16x16x32_bf16 v[4:7], v[18:21], v[22:25], v[4:7]
	ds_read_b128 v[18:21], v9 offset:43648
	ds_read_b128 v[58:61], v9 offset:43712
	s_waitcnt lgkmcnt(1)
	v_mfma_f32_16x16x32_bf16 v[14:17], v[18:21], v[22:25], v[14:17]
	s_waitcnt vmcnt(19)
	ds_write_b128 v8, v[130:133] offset:17408
	s_waitcnt vmcnt(18)
	ds_write_b128 v8, v[134:137] offset:17536
	s_waitcnt vmcnt(17)
	ds_write_b128 v8, v[138:141] offset:52224
	s_waitcnt vmcnt(16)
	ds_write_b128 v8, v[142:145] offset:52352
	s_waitcnt lgkmcnt(0)
	s_barrier
	ds_read_b128 v[26:29], v9 offset:52224
	v_mfma_f32_16x16x32_bf16 v[4:7], v[54:57], v[50:53], v[4:7]
	v_mfma_f32_16x16x32_bf16 v[14:17], v[58:61], v[50:53], v[14:17]
	ds_read_b128 v[30:33], v12
	ds_read_b128 v[50:53], v12 offset:64
	ds_read_b128 v[54:57], v9 offset:52288
	s_waitcnt lgkmcnt(2)
	v_mfma_f32_16x16x32_bf16 v[4:7], v[26:29], v[30:33], v[4:7]
	ds_read_b128 v[26:29], v9 offset:60928
	ds_read_b128 v[58:61], v9 offset:60992
	s_waitcnt lgkmcnt(1)
	v_mfma_f32_16x16x32_bf16 v[14:17], v[26:29], v[30:33], v[14:17]
	ds_read_b128 v[26:29], v9 offset:52352
	v_mfma_f32_16x16x32_bf16 v[4:7], v[54:57], v[50:53], v[4:7]
	s_waitcnt lgkmcnt(1)
	v_mfma_f32_16x16x32_bf16 v[14:17], v[58:61], v[50:53], v[14:17]
	ds_read_b128 v[30:33], v12 offset:128
	ds_read_b128 v[50:53], v12 offset:192
	ds_read_b128 v[54:57], v9 offset:52416
	s_waitcnt lgkmcnt(2)
	v_mfma_f32_16x16x32_bf16 v[4:7], v[26:29], v[30:33], v[4:7]
	ds_read_b128 v[26:29], v9 offset:61056
	ds_read_b128 v[58:61], v9 offset:61120
	s_waitcnt lgkmcnt(1)
	v_mfma_f32_16x16x32_bf16 v[14:17], v[26:29], v[30:33], v[14:17]
	s_waitcnt vmcnt(15)
	ds_write_b128 v8, v[146:149]
	s_waitcnt vmcnt(14)
	ds_write_b128 v8, v[150:153] offset:128
	s_waitcnt vmcnt(13)
	ds_write_b128 v8, v[154:157] offset:34816
	s_waitcnt vmcnt(12)
	ds_write_b128 v8, v[158:161] offset:34944
	s_waitcnt lgkmcnt(0)
	s_barrier
	ds_read_b128 v[34:37], v9 offset:34816
	v_mfma_f32_16x16x32_bf16 v[4:7], v[54:57], v[50:53], v[4:7]
	v_mfma_f32_16x16x32_bf16 v[14:17], v[58:61], v[50:53], v[14:17]
	ds_read_b128 v[38:41], v11
	ds_read_b128 v[50:53], v11 offset:64
	ds_read_b128 v[54:57], v9 offset:34880
	s_waitcnt lgkmcnt(2)
	v_mfma_f32_16x16x32_bf16 v[4:7], v[34:37], v[38:41], v[4:7]
	ds_read_b128 v[34:37], v9 offset:43520
	ds_read_b128 v[58:61], v9 offset:43584
	s_waitcnt lgkmcnt(1)
	v_mfma_f32_16x16x32_bf16 v[14:17], v[34:37], v[38:41], v[14:17]
	ds_read_b128 v[34:37], v9 offset:34944
	v_mfma_f32_16x16x32_bf16 v[4:7], v[54:57], v[50:53], v[4:7]
	s_waitcnt lgkmcnt(1)
	v_mfma_f32_16x16x32_bf16 v[14:17], v[58:61], v[50:53], v[14:17]
	ds_read_b128 v[38:41], v11 offset:128
	ds_read_b128 v[50:53], v11 offset:192
	ds_read_b128 v[54:57], v9 offset:35008
	s_waitcnt lgkmcnt(2)
	v_mfma_f32_16x16x32_bf16 v[4:7], v[34:37], v[38:41], v[4:7]
	ds_read_b128 v[34:37], v9 offset:43648
	ds_read_b128 v[58:61], v9 offset:43712
	s_waitcnt vmcnt(11)
	ds_write_b128 v8, v[164:167] offset:17408
	s_waitcnt vmcnt(10)
	ds_write_b128 v8, v[168:171] offset:17536
	s_waitcnt vmcnt(9)
	ds_write_b128 v8, v[172:175] offset:52224
	s_waitcnt vmcnt(8)
	ds_write_b128 v8, v[176:179] offset:52352
	s_waitcnt lgkmcnt(0)
	v_mfma_f32_16x16x32_bf16 v[14:17], v[34:37], v[38:41], v[14:17]
	s_barrier
	ds_read_b128 v[34:37], v9 offset:52224
	v_mfma_f32_16x16x32_bf16 v[4:7], v[54:57], v[50:53], v[4:7]
	ds_read_b128 v[38:41], v12
	ds_read_b128 v[42:45], v12 offset:64
	ds_read_b128 v[46:49], v9 offset:52288
	v_mfma_f32_16x16x32_bf16 v[14:17], v[58:61], v[50:53], v[14:17]
	s_waitcnt lgkmcnt(2)
	v_mfma_f32_16x16x32_bf16 v[4:7], v[34:37], v[38:41], v[4:7]
	ds_read_b128 v[34:37], v9 offset:60928
	ds_read_b128 v[50:53], v9 offset:60992
	s_waitcnt lgkmcnt(1)
	v_mfma_f32_16x16x32_bf16 v[14:17], v[34:37], v[38:41], v[14:17]
	ds_read_b128 v[34:37], v9 offset:52352
	v_mfma_f32_16x16x32_bf16 v[4:7], v[46:49], v[42:45], v[4:7]
	s_waitcnt lgkmcnt(1)
	v_mfma_f32_16x16x32_bf16 v[14:17], v[50:53], v[42:45], v[14:17]
	ds_read_b128 v[38:41], v12 offset:128
	ds_read_b128 v[42:45], v12 offset:192
	ds_read_b128 v[46:49], v9 offset:52416
	s_waitcnt lgkmcnt(2)
	v_mfma_f32_16x16x32_bf16 v[4:7], v[34:37], v[38:41], v[4:7]
	ds_read_b128 v[34:37], v9 offset:61056
	ds_read_b128 v[50:53], v9 offset:61120
	s_waitcnt vmcnt(7)
	ds_write_b128 v8, v[180:183]
	s_waitcnt vmcnt(6)
	ds_write_b128 v8, v[184:187] offset:128
	s_waitcnt vmcnt(5)
	ds_write_b128 v8, v[188:191] offset:34816
	s_waitcnt vmcnt(4)
	ds_write_b128 v8, v[192:195] offset:34944
	s_waitcnt lgkmcnt(0)
	s_barrier
	ds_read_b128 v[18:21], v9 offset:34816
	v_mfma_f32_16x16x32_bf16 v[14:17], v[34:37], v[38:41], v[14:17]
	ds_read_b128 v[22:25], v11
	ds_read_b128 v[34:37], v11 offset:64
	ds_read_b128 v[38:41], v9 offset:34880
	v_mfma_f32_16x16x32_bf16 v[4:7], v[46:49], v[42:45], v[4:7]
	v_mfma_f32_16x16x32_bf16 v[14:17], v[50:53], v[42:45], v[14:17]
	s_waitcnt lgkmcnt(2)
	v_mfma_f32_16x16x32_bf16 v[4:7], v[18:21], v[22:25], v[4:7]
	ds_read_b128 v[18:21], v9 offset:43520
	ds_read_b128 v[42:45], v9 offset:43584
	s_waitcnt lgkmcnt(1)
	v_mfma_f32_16x16x32_bf16 v[14:17], v[18:21], v[22:25], v[14:17]
	ds_read_b128 v[18:21], v9 offset:34944
	v_mfma_f32_16x16x32_bf16 v[4:7], v[38:41], v[34:37], v[4:7]
	s_waitcnt lgkmcnt(1)
	v_mfma_f32_16x16x32_bf16 v[14:17], v[42:45], v[34:37], v[14:17]
	ds_read_b128 v[22:25], v11 offset:128
	ds_read_b128 v[34:37], v11 offset:192
	ds_read_b128 v[38:41], v9 offset:35008
	s_waitcnt lgkmcnt(2)
	v_mfma_f32_16x16x32_bf16 v[4:7], v[18:21], v[22:25], v[4:7]
	ds_read_b128 v[18:21], v9 offset:43648
	ds_read_b128 v[42:45], v9 offset:43712
	s_waitcnt vmcnt(3)
	ds_write_b128 v8, v[196:199] offset:17408
	s_waitcnt vmcnt(2)
	ds_write_b128 v8, v[206:209] offset:17536
	s_waitcnt vmcnt(1)
	ds_write_b128 v8, v[210:213] offset:52224
	s_waitcnt vmcnt(0)
	ds_write_b128 v8, v[214:217] offset:52352
	s_waitcnt lgkmcnt(0)
	v_mfma_f32_16x16x32_bf16 v[14:17], v[18:21], v[22:25], v[14:17]
	s_barrier
	v_mfma_f32_16x16x32_bf16 v[4:7], v[38:41], v[34:37], v[4:7]
	v_mfma_f32_16x16x32_bf16 v[14:17], v[42:45], v[34:37], v[14:17]
	ds_read_b128 v[18:21], v12
	ds_read_b128 v[22:25], v12 offset:64
	ds_read_b128 v[26:29], v9 offset:52224
	ds_read_b128 v[30:33], v9 offset:52288
	ds_read_b128 v[34:37], v9 offset:60928
	ds_read_b128 v[38:41], v9 offset:60992
	ds_read_b128 v[42:45], v12 offset:128
	ds_read_b128 v[46:49], v12 offset:192
	ds_read_b128 v[50:53], v9 offset:52352
	ds_read_b128 v[54:57], v9 offset:52416
	ds_read_b128 v[58:61], v9 offset:61056
	ds_read_b128 v[62:65], v9 offset:61120
	v_add_u32_e32 v12, s1, v10
	v_lshlrev_b32_e32 v8, 3, v12
	s_waitcnt lgkmcnt(0)
	s_barrier
	global_load_dwordx2 v[66:67], v8, s[4:5]
	v_lshlrev_b32_e32 v8, 2, v1
	v_or3_b32 v13, v8, v2, s0
	v_readlane_b32 s0, v251, 48
	v_lshlrev_b32_e32 v2, 11, v12
	v_readlane_b32 s1, v251, 49
	v_mfma_f32_16x16x32_bf16 v[4:7], v[26:29], v[18:21], v[4:7]
	s_nop 0
	v_lshl_add_u64 v[8:9], s[0:1], 0, v[2:3]
	v_lshlrev_b32_e32 v2, 1, v13
	v_lshl_add_u64 v[26:27], v[8:9], 0, v[2:3]
	global_load_dwordx2 v[68:69], v[26:27], off
	v_lshlrev_b32_e32 v2, 2, v13
	v_mfma_f32_16x16x32_bf16 v[8:11], v[34:37], v[18:21], v[14:17]
	s_nop 2
	global_load_dwordx4 v[14:17], v2, s[38:39]
	global_load_dwordx4 v[18:21], v2, s[40:41]
	global_load_dwordx2 v[34:35], v[26:27], off offset:64
	v_mbcnt_lo_u32_b32 v3, -1, 0
	v_mfma_f32_16x16x32_bf16 v[4:7], v[30:33], v[22:25], v[4:7]
	v_mbcnt_hi_u32_b32 v3, -1, v3
	s_mov_b32 s0, 0x3a800000
	v_and_b32_e32 v30, 64, v3
	v_mfma_f32_16x16x32_bf16 v[8:11], v[38:41], v[22:25], v[8:11]
	global_load_dwordx4 v[22:25], v2, s[38:39] offset:128
	global_load_dwordx4 v[26:29], v2, s[40:41] offset:128
	v_xor_b32_e32 v13, 16, v3
	v_add_u32_e32 v40, 64, v30
	v_cmp_lt_i32_e32 vcc, v13, v40
	v_mfma_f32_16x16x32_bf16 v[8:11], v[58:61], v[42:45], v[8:11]
	v_xor_b32_e32 v41, 32, v3
	v_cndmask_b32_e32 v13, v3, v13, vcc
	v_lshlrev_b32_e32 v13, 2, v13
	v_mfma_f32_16x16x32_bf16 v[4:7], v[50:53], v[42:45], v[4:7]
	s_waitcnt vmcnt(6)
	v_pk_mul_f32 v[36:37], v[66:67], s[0:1] op_sel_hi:[1,0]
	s_nop 0
	v_fma_f32 v30, -v36, v36, v37
	v_add_f32_e32 v30, 0x3727c5ac, v30
	s_mov_b32 s0, 0x800000
	v_mul_f32_e32 v31, 0x4b800000, v30
	v_cmp_gt_f32_e32 vcc, s0, v30
	v_mfma_f32_16x16x32_bf16 v[4:7], v[54:57], v[46:49], v[4:7]
	s_mov_b32 s0, 0x3f9837f0
	v_cndmask_b32_e32 v30, v30, v31, vcc
	v_rsq_f32_e32 v37, v30
	v_mfma_f32_16x16x32_bf16 v[30:33], v[62:65], v[46:49], v[8:11]
	s_waitcnt vmcnt(5)
	v_and_b32_e32 v38, 0xffff0000, v69
	v_sub_f32_e32 v39, v38, v36
	v_mul_f32_e32 v8, 0x45800000, v37
	v_cndmask_b32_e32 v8, v37, v8, vcc
	v_lshlrev_b32_e32 v9, 16, v68
	v_and_b32_e32 v10, 0xffff0000, v68
	v_lshlrev_b32_e32 v37, 16, v69
	v_sub_f32_e32 v11, v10, v36
	v_sub_f32_e32 v10, v9, v36
	v_sub_f32_e32 v38, v37, v36
	v_pk_mul_f32 v[38:39], v[38:39], v[8:9] op_sel_hi:[1,0]
	v_pk_mul_f32 v[10:11], v[10:11], v[8:9] op_sel_hi:[1,0]
	v_cmp_lt_i32_e32 vcc, v41, v40
	s_waitcnt vmcnt(3)
	v_pk_fma_f32 v[10:11], v[14:15], v[10:11], v[18:19]
	v_pk_fma_f32 v[14:15], v[16:17], v[38:39], v[20:21]
	v_pk_fma_f32 v[4:5], v[10:11], s[0:1], v[4:5] op_sel_hi:[1,0,1]
	v_pk_fma_f32 v[6:7], v[14:15], s[0:1], v[6:7] op_sel_hi:[1,0,1]
	v_add_f32_e32 v9, v4, v5
	v_add_f32_e32 v10, v6, v7
	v_add_f32_e32 v9, v9, v10
	v_add_f32_e32 v16, 0, v9
	v_mul_f32_e32 v9, v5, v5
	v_mul_f32_e32 v10, v7, v7
	v_fmac_f32_e32 v9, v4, v4
	v_fmac_f32_e32 v10, v6, v6
	v_add_f32_e32 v17, v9, v10
	s_waitcnt vmcnt(2)
	v_lshlrev_b32_e32 v9, 16, v34
	v_and_b32_e32 v10, 0xffff0000, v34
	v_lshlrev_b32_e32 v14, 16, v35
	v_and_b32_e32 v15, 0xffff0000, v35
	v_sub_f32_e32 v11, v10, v36
	v_sub_f32_e32 v10, v9, v36
	v_sub_f32_e32 v15, v15, v36
	v_sub_f32_e32 v14, v14, v36
	v_pk_mul_f32 v[14:15], v[8:9], v[14:15] op_sel_hi:[0,1]
	v_pk_mul_f32 v[8:9], v[8:9], v[10:11] op_sel_hi:[0,1]
	s_waitcnt vmcnt(0)
	v_pk_fma_f32 v[10:11], v[22:23], v[8:9], v[26:27]
	v_pk_fma_f32 v[8:9], v[24:25], v[14:15], v[28:29]
	v_pk_fma_f32 v[10:11], v[10:11], s[0:1], v[30:31] op_sel_hi:[1,0,1]
	v_pk_fma_f32 v[8:9], v[8:9], s[0:1], v[32:33] op_sel_hi:[1,0,1]
	v_add_f32_e32 v14, v10, v11
	v_add_f32_e32 v15, v8, v9
	v_add_f32_e32 v14, v14, v15
	v_add_f32_e32 v14, v16, v14
	v_mul_f32_e32 v15, v11, v11
	v_mul_f32_e32 v16, v9, v9
	v_fmac_f32_e32 v15, v10, v10
	v_fmac_f32_e32 v16, v8, v8
	v_add_f32_e32 v15, v15, v16
	v_add_f32_e32 v15, v17, v15
	ds_bpermute_b32 v16, v13, v14
	ds_bpermute_b32 v17, v13, v15
	v_cndmask_b32_e32 v3, v3, v41, vcc
	v_lshlrev_b32_e32 v18, 2, v3
	v_cmp_eq_u32_e32 vcc, 0, v1
	s_waitcnt lgkmcnt(1)
	v_add_f32_e32 v3, v14, v16
	s_waitcnt lgkmcnt(0)
	v_add_f32_e32 v14, v15, v17
	ds_bpermute_b32 v13, v18, v3
	ds_bpermute_b32 v15, v18, v14
	v_lshlrev_b32_e32 v1, 1, v12
	v_lshlrev_b32_e32 v1, 2, v1
	s_and_saveexec_b64 s[0:1], vcc
	s_cbranch_execz .LBB0_1310
	s_waitcnt lgkmcnt(1)
	v_add_f32_e32 v3, v3, v13
	s_waitcnt lgkmcnt(0)
	v_add_f32_e32 v13, v14, v15
	global_atomic_add_f32 v1, v3, s[82:83]
	global_atomic_add_f32 v1, v13, s[82:83] offset:4
